# P1 rmsnorm+modulate: scale/shift vectors of column chunks 1..7 fetched at the top of the row iteration with counted waits instead of a load pair + wait per chunk behind the previous store, on v219
# speedup vs baseline: 1.0020x; 1.0007x over previous
.LBB0_196:
	global_load_dwordx4 v[46:49], v[58:59], off offset:-2048 nt
	global_load_dwordx4 v[38:41], v[58:59], off offset:1024 nt
	global_load_dwordx4 v[78:81], v[58:59], off offset:-4096 nt
	global_load_dwordx4 v[82:85], v[58:59], off offset:-3072 nt
	global_load_dwordx4 v[54:57], v[58:59], off offset:-1024 nt
	global_load_dwordx4 v[50:53], v[58:59], off nt
	global_load_dwordx4 v[42:45], v[58:59], off offset:2048 nt
	global_load_dwordx4 v[34:37], v[58:59], off offset:3072 nt
	s_ashr_i32 s10, s14, 12
	s_mul_hi_i32 s11, s10, 0x12000
	s_mul_i32 s10, s10, 0x12000
	s_add_u32 s10, s50, s10
	s_addc_u32 s11, s51, s11
	s_add_u32 s12, s10, 0x2000
	s_addc_u32 s13, s11, 0
	global_load_dwordx4 v[86:89], v69, s[12:13]
	global_load_dwordx4 v[90:93], v69, s[10:11]
	global_load_dwordx4 v[126:129], v70, s[12:13]
	global_load_dwordx4 v[130:133], v69, s[10:11] offset:1024
	global_load_dwordx4 v[134:137], v71, s[12:13]
	global_load_dwordx4 v[138:141], v69, s[10:11] offset:2048
	global_load_dwordx4 v[142:145], v72, s[12:13]
	global_load_dwordx4 v[146:149], v69, s[10:11] offset:3072
	global_load_dwordx4 v[150:153], v73, s[12:13]
	global_load_dwordx4 v[154:157], v73, s[10:11]
	global_load_dwordx4 v[158:161], v74, s[12:13]
	global_load_dwordx4 v[162:165], v74, s[10:11]
	global_load_dwordx4 v[166:169], v75, s[12:13]
	global_load_dwordx4 v[170:173], v75, s[10:11]
	global_load_dwordx4 v[174:177], v76, s[12:13]
	global_load_dwordx4 v[178:181], v76, s[10:11]
	s_add_i32 s14, s14, s101
	v_lshl_add_u64 v[58:59], v[58:59], 0, s[0:1]
	s_cmp_lt_i32 s14, s100
	s_waitcnt vmcnt(23)
	v_pk_mul_f32 v[94:95], v[48:49], v[48:49]
	v_pk_mul_f32 v[96:97], v[46:47], v[46:47]
	s_waitcnt vmcnt(22)
	v_pk_mul_f32 v[98:99], v[40:41], v[40:41]
	v_pk_mul_f32 v[100:101], v[38:39], v[38:39]
	s_waitcnt vmcnt(21)
	v_mov_b32_e32 v104, v79
	s_waitcnt vmcnt(20)
	v_mov_b32_e32 v105, v83
	v_mov_b32_e32 v108, v81
	v_mov_b32_e32 v109, v85
	v_mov_b32_e32 v102, v78
	v_mov_b32_e32 v103, v82
	v_mov_b32_e32 v106, v80
	v_mov_b32_e32 v107, v84
	v_pk_mov_b32 v[118:119], v[96:97], v[94:95] op_sel:[1,0]
	v_mov_b32_e32 v97, v95
	v_pk_mov_b32 v[94:95], v[100:101], v[98:99] op_sel:[1,0]
	v_mov_b32_e32 v101, v99
	v_pk_mul_f32 v[98:99], v[104:105], v[104:105]
	v_pk_mul_f32 v[104:105], v[108:109], v[108:109]
	v_pk_fma_f32 v[98:99], v[102:103], v[102:103], v[98:99]
	v_pk_fma_f32 v[102:103], v[106:107], v[106:107], v[104:105]
	s_waitcnt vmcnt(19)
	v_mul_f32_e32 v110, v55, v55
	v_mul_f32_e32 v112, v57, v57
	v_pk_add_f32 v[96:97], v[118:119], v[96:97]
	v_pk_add_f32 v[98:99], v[98:99], v[102:103]
	s_waitcnt vmcnt(18)
	v_mul_f32_e32 v77, v52, v52
	v_mul_f32_e32 v117, v53, v53
	v_mul_f32_e32 v122, v51, v51
	v_mul_f32_e32 v123, v50, v50
	v_pk_fma_f32 v[108:109], v[54:55], v[54:55], v[110:111] op_sel_hi:[1,1,0]
	v_pk_fma_f32 v[110:111], v[56:57], v[56:57], v[112:113] op_sel_hi:[1,1,0]
	v_pk_add_f32 v[96:97], v[96:97], v[96:97] op_sel:[0,1] op_sel_hi:[1,0]
	v_pk_add_f32 v[98:99], v[98:99], v[98:99] op_sel:[0,1] op_sel_hi:[1,0]
	v_mov_b32_e32 v109, v77
	v_mov_b32_e32 v111, v117
	v_mov_b32_e32 v97, v122
	v_mov_b32_e32 v99, v123
	v_pk_add_f32 v[94:95], v[94:95], v[100:101]
	v_pk_add_f32 v[100:101], v[108:109], v[110:111]
	v_pk_add_f32 v[96:97], v[98:99], v[96:97]
	s_waitcnt vmcnt(17)
	v_mul_f32_e32 v114, v43, v43
	v_mul_f32_e32 v116, v45, v45
	v_pk_add_f32 v[96:97], v[96:97], v[100:101]
	s_waitcnt vmcnt(16)
	v_mul_f32_e32 v120, v36, v36
	v_mul_f32_e32 v121, v37, v37
	v_mul_f32_e32 v124, v35, v35
	v_mul_f32_e32 v125, v34, v34
	v_pk_fma_f32 v[112:113], v[42:43], v[42:43], v[114:115] op_sel_hi:[1,1,0]
	v_pk_fma_f32 v[114:115], v[44:45], v[44:45], v[116:117] op_sel_hi:[1,1,0]
	v_pk_add_f32 v[94:95], v[94:95], v[94:95] op_sel:[0,1] op_sel_hi:[1,0]
	v_pk_add_f32 v[96:97], v[96:97], v[96:97] op_sel:[0,1] op_sel_hi:[1,0]
	v_mov_b32_e32 v113, v120
	v_mov_b32_e32 v115, v121
	v_mov_b32_e32 v95, v124
	v_mov_b32_e32 v97, v125
	v_pk_add_f32 v[102:103], v[112:113], v[114:115]
	v_pk_add_f32 v[94:95], v[96:97], v[94:95]
	s_waitcnt vmcnt(15)
	v_pk_add_f32 v[88:89], v[88:89], 1.0 op_sel_hi:[1,0]
	v_pk_add_f32 v[94:95], v[94:95], v[102:103]
	v_pk_add_f32 v[86:87], v[86:87], 1.0 op_sel_hi:[1,0]
	v_add_f32_e32 v77, v94, v95
	ds_bpermute_b32 v94, v62, v77
	s_waitcnt lgkmcnt(0)
	v_add_f32_e32 v77, v77, v94
	ds_bpermute_b32 v94, v63, v77
	s_waitcnt lgkmcnt(0)
	v_add_f32_e32 v77, v77, v94
	ds_bpermute_b32 v94, v64, v77
	s_waitcnt lgkmcnt(0)
	v_add_f32_e32 v77, v77, v94
	ds_bpermute_b32 v94, v65, v77
	s_waitcnt lgkmcnt(0)
	v_add_f32_e32 v77, v77, v94
	ds_bpermute_b32 v94, v66, v77
	s_waitcnt lgkmcnt(0)
	v_add_f32_e32 v77, v77, v94
	ds_bpermute_b32 v94, v67, v77
	s_waitcnt lgkmcnt(0)
	v_add_f32_e32 v77, v77, v94
	v_fmamk_f32 v77, v77, 0x3a000000, v68
	v_rsq_f32_e32 v94, v77
	s_nop 0
	v_pk_mul_f32 v[80:81], v[80:81], v[94:95] op_sel_hi:[1,0]
	v_pk_mul_f32 v[78:79], v[78:79], v[94:95] op_sel_hi:[1,0]
	v_pk_mul_f32 v[80:81], v[4:5], v[80:81]
	v_pk_mul_f32 v[78:79], v[2:3], v[78:79]
	s_waitcnt vmcnt(14)
	v_pk_fma_f32 v[80:81], v[88:89], v[80:81], v[92:93]
	v_pk_fma_f32 v[78:79], v[86:87], v[78:79], v[90:91]
	v_pk_mul_f32 v[84:85], v[84:85], v[94:95] op_sel_hi:[1,0]
	v_cvt_pk_bf16_f32 v78, v78, v79
	v_cvt_pk_bf16_f32 v79, v80, v81
	global_store_dwordx2 v[60:61], v[78:79], off
	v_pk_mul_f32 v[82:83], v[82:83], v[94:95] op_sel_hi:[1,0]
	v_pk_mul_f32 v[84:85], v[8:9], v[84:85]
	v_pk_mul_f32 v[82:83], v[6:7], v[82:83]
	v_pk_mul_f32 v[48:49], v[48:49], v[94:95] op_sel_hi:[1,0]
	v_pk_mul_f32 v[46:47], v[46:47], v[94:95] op_sel_hi:[1,0]
	v_pk_mul_f32 v[48:49], v[12:13], v[48:49]
	v_pk_mul_f32 v[46:47], v[10:11], v[46:47]
	v_pk_mul_f32 v[56:57], v[56:57], v[94:95] op_sel_hi:[1,0]
	v_pk_mul_f32 v[54:55], v[54:55], v[94:95] op_sel_hi:[1,0]
	v_pk_mul_f32 v[56:57], v[16:17], v[56:57]
	v_pk_mul_f32 v[54:55], v[14:15], v[54:55]
	v_pk_mul_f32 v[52:53], v[52:53], v[94:95] op_sel_hi:[1,0]
	v_pk_mul_f32 v[50:51], v[50:51], v[94:95] op_sel_hi:[1,0]
	v_pk_mul_f32 v[52:53], v[20:21], v[52:53]
	v_pk_mul_f32 v[50:51], v[18:19], v[50:51]
	v_pk_mul_f32 v[40:41], v[40:41], v[94:95] op_sel_hi:[1,0]
	v_pk_mul_f32 v[38:39], v[38:39], v[94:95] op_sel_hi:[1,0]
	v_pk_mul_f32 v[40:41], v[24:25], v[40:41]
	v_pk_mul_f32 v[38:39], v[22:23], v[38:39]
	v_pk_mul_f32 v[44:45], v[44:45], v[94:95] op_sel_hi:[1,0]
	v_pk_mul_f32 v[42:43], v[42:43], v[94:95] op_sel_hi:[1,0]
	v_pk_mul_f32 v[44:45], v[28:29], v[44:45]
	v_pk_mul_f32 v[42:43], v[26:27], v[42:43]
	v_pk_mul_f32 v[36:37], v[36:37], v[94:95] op_sel_hi:[1,0]
	v_pk_mul_f32 v[34:35], v[34:35], v[94:95] op_sel_hi:[1,0]
	v_pk_mul_f32 v[36:37], v[32:33], v[36:37]
	v_pk_mul_f32 v[34:35], v[30:31], v[34:35]
	s_waitcnt vmcnt(14)
	v_pk_add_f32 v[80:81], v[128:129], 1.0 op_sel_hi:[1,0]
	v_pk_add_f32 v[78:79], v[126:127], 1.0 op_sel_hi:[1,0]
	s_waitcnt vmcnt(13)
	v_pk_fma_f32 v[80:81], v[80:81], v[84:85], v[132:133]
	v_pk_fma_f32 v[78:79], v[78:79], v[82:83], v[130:131]
	s_nop 0
	v_cvt_pk_bf16_f32 v78, v78, v79
	v_cvt_pk_bf16_f32 v79, v80, v81
	global_store_dwordx2 v[60:61], v[78:79], off offset:512
	s_waitcnt vmcnt(13)
	v_pk_add_f32 v[80:81], v[136:137], 1.0 op_sel_hi:[1,0]
	v_pk_add_f32 v[78:79], v[134:135], 1.0 op_sel_hi:[1,0]
	s_waitcnt vmcnt(12)
	v_pk_fma_f32 v[48:49], v[80:81], v[48:49], v[140:141]
	v_pk_fma_f32 v[46:47], v[78:79], v[46:47], v[138:139]
	s_nop 0
	v_cvt_pk_bf16_f32 v46, v46, v47
	v_cvt_pk_bf16_f32 v47, v48, v49
	global_store_dwordx2 v[60:61], v[46:47], off offset:1024
	s_waitcnt vmcnt(12)
	v_pk_add_f32 v[48:49], v[144:145], 1.0 op_sel_hi:[1,0]
	v_pk_add_f32 v[46:47], v[142:143], 1.0 op_sel_hi:[1,0]
	s_waitcnt vmcnt(11)
	v_pk_fma_f32 v[48:49], v[48:49], v[56:57], v[148:149]
	v_pk_fma_f32 v[46:47], v[46:47], v[54:55], v[146:147]
	s_nop 0
	v_cvt_pk_bf16_f32 v46, v46, v47
	v_cvt_pk_bf16_f32 v47, v48, v49
	global_store_dwordx2 v[60:61], v[46:47], off offset:1536
	s_waitcnt vmcnt(11)
	v_pk_add_f32 v[48:49], v[152:153], 1.0 op_sel_hi:[1,0]
	v_pk_add_f32 v[46:47], v[150:151], 1.0 op_sel_hi:[1,0]
	s_waitcnt vmcnt(10)
	v_pk_fma_f32 v[48:49], v[52:53], v[48:49], v[156:157]
	v_pk_fma_f32 v[46:47], v[50:51], v[46:47], v[154:155]
	s_nop 0
	v_cvt_pk_bf16_f32 v46, v46, v47
	v_cvt_pk_bf16_f32 v47, v48, v49
	global_store_dwordx2 v[60:61], v[46:47], off offset:2048
	s_waitcnt vmcnt(10)
	v_pk_add_f32 v[48:49], v[160:161], 1.0 op_sel_hi:[1,0]
	v_pk_add_f32 v[46:47], v[158:159], 1.0 op_sel_hi:[1,0]
	s_waitcnt vmcnt(9)
	v_pk_fma_f32 v[40:41], v[40:41], v[48:49], v[164:165]
	v_pk_fma_f32 v[38:39], v[38:39], v[46:47], v[162:163]
	s_nop 0
	v_cvt_pk_bf16_f32 v38, v38, v39
	v_cvt_pk_bf16_f32 v39, v40, v41
	global_store_dwordx2 v[60:61], v[38:39], off offset:2560
	s_waitcnt vmcnt(9)
	v_pk_add_f32 v[40:41], v[168:169], 1.0 op_sel_hi:[1,0]
	v_pk_add_f32 v[38:39], v[166:167], 1.0 op_sel_hi:[1,0]
	s_waitcnt vmcnt(8)
	v_pk_fma_f32 v[40:41], v[44:45], v[40:41], v[172:173]
	v_pk_fma_f32 v[38:39], v[42:43], v[38:39], v[170:171]
	s_nop 0
	v_cvt_pk_bf16_f32 v38, v38, v39
	v_cvt_pk_bf16_f32 v39, v40, v41
	global_store_dwordx2 v[60:61], v[38:39], off offset:3072
	s_waitcnt vmcnt(8)
	v_pk_add_f32 v[40:41], v[176:177], 1.0 op_sel_hi:[1,0]
	v_pk_add_f32 v[38:39], v[174:175], 1.0 op_sel_hi:[1,0]
	s_waitcnt vmcnt(7)
	v_pk_fma_f32 v[36:37], v[36:37], v[40:41], v[180:181]
	v_pk_fma_f32 v[34:35], v[34:35], v[38:39], v[178:179]
	s_nop 0
	v_cvt_pk_bf16_f32 v34, v34, v35
	v_cvt_pk_bf16_f32 v35, v36, v37
	global_store_dwordx2 v[60:61], v[34:35], off offset:3584
	v_lshl_add_u64 v[60:61], v[60:61], 0, s[6:7]
	s_cbranch_scc1 .LBB0_196
